# non-GEMM phases skip the 8-iteration GEMM-kind dispatch loop at the top of each phase (about 240 scalar instructions per phase)
# speedup vs baseline: 1.0159x; 1.0063x over previous
.LBB0_165:
	s_add_i32 s0, s36, 9
	s_add_u32 s71, s4, 0x3800000
	s_addc_u32 s72, s5, 0
	s_cmp_lt_u32 s0, 21
	v_writelane_b32 v245, s36, 37
	s_cselect_b64 s[0:1], -1, 0
	v_writelane_b32 v245, s0, 38
	s_mov_b32 s24, 0
	s_nop 0
	v_writelane_b32 v245, s1, 39
	s_and_b64 s[0:1], s[0:1], exec
	s_cselect_b32 s7, 0, 0x400
	s_cselect_b32 s100, 1, 0
	s_mov_b32 s101, 0x900
	s_bitcmp1_b32 s101, s36
	s_cselect_b32 s7, 0x400, s7
	s_cmp_eq_u32 s100, 1
	v_writelane_b32 v245, s7, 40
	s_cselect_b32 s0, s16, s71
	v_writelane_b32 v245, s0, 41
	s_cselect_b32 s0, s17, s72
	s_xor_b32 s46, s7, 0x4400
	s_mul_i32 s1, s70, 0x1600000
	v_writelane_b32 v245, s0, 42
	s_mul_hi_i32 s0, s70, 0x1600000
	s_add_u32 s1, s4, s1
	s_addc_u32 s0, s5, s0
	s_add_u32 s8, s1, 0xc00000
	s_addc_u32 s9, s0, 0
	v_writelane_b32 v245, s8, 43
	s_nop 1
	v_writelane_b32 v245, s9, 44
	s_add_u32 s8, s4, 0x3c00000
	s_addc_u32 s9, s5, 0
	s_lshl_b32 s6, s7, 11
	s_add_u32 s10, s8, s6
	v_writelane_b32 v245, s8, 45
	s_addc_u32 s11, s9, 0
	s_nop 0
	v_writelane_b32 v245, s9, 46
	v_writelane_b32 v245, s10, 47
	s_add_u32 s8, s1, 0x1000000
	s_addc_u32 s9, s0, 0
	v_writelane_b32 v245, s11, 48
	v_writelane_b32 v245, s8, 49
	s_nop 1
	v_writelane_b32 v245, s9, 50
	s_add_u32 s8, s1, 0x1200000
	s_addc_u32 s9, s0, 0
	v_writelane_b32 v245, s8, 51
	s_nop 1
	v_writelane_b32 v245, s9, 52
	s_add_u32 s8, s4, 0xc500000
	s_addc_u32 s9, s5, 0
	s_lshl_b32 s6, s7, 9
	s_add_u32 s10, s8, s6
	v_writelane_b32 v245, s8, 53
	s_addc_u32 s11, s9, 0
	s_nop 0
	v_writelane_b32 v245, s9, 54
	v_writelane_b32 v245, s10, 55
	s_add_u32 s8, s1, 0xfc0000
	s_addc_u32 s9, s0, 0
	v_writelane_b32 v245, s11, 56
	v_writelane_b32 v245, s8, 57
	s_nop 1
	v_writelane_b32 v245, s9, 58
	s_add_u32 s8, s4, 0xbc00000
	s_addc_u32 s9, s5, 0
	v_writelane_b32 v245, s8, 59
	s_add_u32 s8, s8, s6
	v_writelane_b32 v245, s9, 60
	s_addc_u32 s9, s9, 0
	v_writelane_b32 v245, s8, 61
	s_nop 1
	v_writelane_b32 v245, s9, 62
	s_add_u32 s8, s1, 0xfa0000
	s_addc_u32 s9, s0, 0
	v_writelane_b32 v245, s8, 63
	s_nop 1
	v_writelane_b32 v244, s9, 0
	s_add_u32 s8, s4, 0xa300000
	s_addc_u32 s9, s5, 0
	s_add_u32 s10, s8, s6
	v_writelane_b32 v244, s8, 1
	s_addc_u32 s11, s9, 0
	s_nop 0
	v_writelane_b32 v244, s9, 2
	v_writelane_b32 v244, s10, 3
	s_add_u32 s8, s1, 0xf80000
	s_addc_u32 s9, s0, 0
	v_writelane_b32 v244, s11, 4
	v_writelane_b32 v244, s8, 5
	s_nop 1
	v_writelane_b32 v244, s9, 6
	s_add_u32 s8, s1, 0xe80000
	s_addc_u32 s9, s0, 0
	v_writelane_b32 v244, s8, 7
	s_nop 1
	v_writelane_b32 v244, s9, 8
	s_add_u32 s8, s4, 0x5e00000
	s_addc_u32 s9, s5, 0
	s_lshl_b32 s6, s7, 13
	s_add_u32 s10, s8, s6
	v_writelane_b32 v247, s8, 26
	s_addc_u32 s11, s9, 0
	v_writelane_b32 v244, s10, 9
	v_writelane_b32 v247, s9, 27
	s_add_u32 s8, s1, 0x1a00000
	s_addc_u32 s9, s0, 0
	s_lshl_b32 s0, s70, 10
	v_writelane_b32 v244, s11, 10
	s_ashr_i32 s1, s0, 31
	v_writelane_b32 v244, s8, 11
	s_lshr_b32 s47, s7, 8
	s_lshl_b64 s[0:1], s[0:1], 2
	v_writelane_b32 v244, s9, 12
	s_add_u32 s6, s4, s0
	v_writelane_b32 v244, s6, 13
	v_writelane_b32 v244, s0, 14
	s_nop 1
	v_writelane_b32 v244, s1, 15
	s_addc_u32 s0, s5, s1
	v_writelane_b32 v244, s0, 16
	s_add_u32 s0, s4, 0xce00000
	s_addc_u32 s1, s5, 0
	v_writelane_b32 v244, s0, 17
	s_nop 1
	v_writelane_b32 v244, s1, 18
	s_lshl_b32 s0, s70, 9
	s_ashr_i32 s1, s0, 31
	s_lshl_b64 s[0:1], s[0:1], 2
	s_add_u32 s0, s4, s0
	s_addc_u32 s1, s5, s1
	s_add_u32 s0, s0, 0x220320
	s_addc_u32 s1, s1, 0
	v_writelane_b32 v244, s0, 19
	s_lshl_b32 s6, s70, 8
	s_ashr_i32 s7, s6, 31
	v_writelane_b32 v244, s1, 20
	s_mov_b32 s0, s6
	v_writelane_b32 v244, s0, 21
	s_lshl_b64 s[6:7], s[6:7], 2
	s_nop 0
	v_writelane_b32 v244, s1, 22
	s_add_u32 s0, s4, s6
	v_writelane_b32 v244, s6, 23
	s_addc_u32 s1, s5, s7
	s_add_u32 s8, s0, 0x113800
	s_addc_u32 s9, s1, 0
	s_add_u32 s28, s4, 0xdf00000
	s_addc_u32 s29, s5, 0
	s_add_u32 s84, s0, 0x113000
	s_addc_u32 s85, s1, 0
	v_writelane_b32 v244, s7, 24
	s_add_u32 s0, s4, 0x9a00000
	v_writelane_b32 v244, s0, 25
	s_addc_u32 s0, s5, 0
	v_writelane_b32 v244, s0, 26
	s_add_u32 s0, s4, 0xa200000
	v_writelane_b32 v247, s0, 25
	s_addc_u32 s0, s5, 0
	v_writelane_b32 v244, s0, 27
	s_lshl_b32 s0, s70, 12
	s_ashr_i32 s1, s0, 31
	s_lshl_b64 s[0:1], s[0:1], 2
	s_add_u32 s0, s4, s0
	s_addc_u32 s1, s5, s1
	s_add_u32 s0, s0, 0x227320
	s_addc_u32 s1, s1, 0
	v_writelane_b32 v244, s0, 28
	v_writelane_b32 v247, s70, 28
	s_nop 0
	v_writelane_b32 v244, s1, 29
	v_writelane_b32 v244, s71, 30
	v_writelane_b32 v244, s72, 31
	s_and_b32 s0, s94, 0x6a906
	s_cmp_lg_u32 s0, 0
	s_cbranch_scc1 .LBB0_168
	s_mov_b32 s24, 8
	s_mov_b64 s[14:15], 0
	s_mov_b32 s6, 0
	s_mov_b64 s[0:1], -1
	s_mov_b64 vcc, exec
	s_cmp_eq_u32 s24, 8
	s_branch .LBB0_342
